# gMLP items pipelined on the attention->gMLP path: next index published at the item's first barrier, next item's nine loads issued behind it into a second register set; one barrier per item fewer
# speedup vs baseline: 1.0032x; 1.0032x over previous
.Lgq_entry:
	s_mov_b32 s72, 1
	s_load_dwordx2 s[4:5], s[0:1], 0xe0
	s_waitcnt lgkmcnt(0)
	s_add_u32 s8, s4, 0x3600
	s_addc_u32 s9, s5, 0
	s_and_saveexec_b64 s[4:5], s[44:45]
	s_cbranch_execz .Lgq_379
	v_readfirstlane_b32 s3, v252
	v_mov_b32_e32 v2, 0
	s_nop 0
	v_mov_b32_e32 v1, s3
	ds_write_b32 v2, v1 offset:8

.LBB0_375:
	s_mov_b32 s72, 0
	s_load_dwordx2 s[4:5], s[0:1], 0xe0
	s_waitcnt lgkmcnt(0)
	s_add_u32 s8, s4, 0x3600
	s_addc_u32 s9, s5, 0
	s_and_saveexec_b64 s[4:5], s[44:45]
	s_cbranch_execz .LBB0_379
	s_mov_b64 s[10:11], exec
	s_waitcnt vmcnt(0)
	v_mbcnt_lo_u32_b32 v1, s10, 0
	v_mbcnt_hi_u32_b32 v1, s11, v1
	v_cmp_eq_u32_e32 vcc, 0, v1
	s_and_saveexec_b64 s[6:7], vcc
	s_cbranch_execz .LBB0_378
	s_bcnt1_i32_b64 s3, s[10:11]
	v_mov_b32_e32 v2, 0
	v_mov_b32_e32 v3, s3
	global_atomic_add v2, v2, v3, s[8:9] sc0

.Lgq_join:
	ds_read_b32 v1, v43 offset:8
	s_waitcnt lgkmcnt(0)
	v_readfirstlane_b32 s14, v1
	s_cmpk_gt_i32 s14, 0x1ff
	s_cbranch_scc1 .LBB0_396
	s_load_dwordx2 s[10:11], s[0:1], 0x90
	s_load_dwordx2 s[16:17], s[58:59], 0x0
	s_load_dwordx2 s[12:13], s[0:1], 0x30
	s_load_dwordx4 s[4:7], s[0:1], 0xc0
	s_mov_b32 s15, 0
	s_movk_i32 s3, 0x1a00
	s_waitcnt lgkmcnt(0)
	v_mov_b64_e32 v[44:45], s[16:17]
	s_movk_i32 s22, 0x90
	v_mbcnt_hi_u32_b32 v1, -1, v176
	s_cmp_eq_u32 s72, 1
	s_cbranch_scc1 .Lp_pre
	s_branch .LBB0_382

.Lp_pre:
	s_mov_b32 s62, s14
	s_mov_b32 s63, 0
	v_mov_b32_e32 v143, 0
	v_mov_b32_e32 v147, 0
	v_mov_b32_e32 v151, v0
	s_and_b32 s66, s62, 3
	s_ashr_i32 s64, s62, 7
	s_lshl_b32 s62, s62, 5
	v_ashrrev_i32_e32 v102, 2, v151
	s_ashr_i32 s65, s64, 31
	s_and_b32 s62, s62, 0xf80
	v_bfi_b32 v102, -16, v102, v151
	s_lshl_b32 s67, s66, 15
	s_add_u32 s68, s10, s67
	v_ashrrev_i32_e32 v103, 31, v102
	v_lshrrev_b32_e32 v106, 1, v151
	s_addc_u32 s69, s11, 0
	v_lshlrev_b64 v[104:105], 8, v[102:103]
	v_and_b32_e32 v162, 24, v106
	v_lshl_add_u64 v[104:105], s[68:69], 0, v[104:105]
	v_lshlrev_b32_e32 v142, 1, v162
	s_lshl_b64 s[64:65], s[64:65], 12
	v_lshl_add_u64 v[104:105], v[104:105], 0, v[142:143]
	s_or_b32 s64, s64, s62
	s_lshl_b32 s62, s66, 7
	global_load_dwordx4 v[138:141], v[104:105], off
	global_load_dwordx4 v[134:137], v[104:105], off offset:64
	global_load_dwordx4 v[122:125], v[104:105], off offset:128
	global_load_dwordx4 v[110:113], v[104:105], off offset:192
	v_add_u32_e32 v104, s62, v102
	v_ashrrev_i32_e32 v105, 31, v104
	v_lshl_add_u64 v[104:105], v[104:105], 2, s[12:13]
	global_load_dword v146, v[104:105], off
	v_and_b32_e32 v150, 16, v151
	v_lshrrev_b32_e32 v104, 2, v151
	v_ashrrev_i32_e32 v158, 3, v151
	v_and_or_b32 v114, v104, 8, v150
	v_lshlrev_b32_e32 v104, 4, v151
	v_ashrrev_i32_e32 v159, 31, v158
	v_and_b32_e32 v152, 0x70, v104
	v_lshl_add_u64 v[104:105], s[64:65], 0, v[158:159]
	v_mad_u64_u32 v[106:107], s[68:69], v104, s3, v[44:45]
	v_mad_i32_i24 v107, v105, s3, v107
	v_lshl_add_u64 v[104:105], v[106:107], 0, s[62:63]
	v_add_u32_e32 v106, 0x200, v151
	v_ashrrev_i32_e32 v160, 3, v106
	v_ashrrev_i32_e32 v161, 31, v160
	v_lshl_add_u64 v[106:107], s[64:65], 0, v[160:161]
	v_lshl_add_u64 v[148:149], s[64:65], 0, v[102:103]
	v_mad_u64_u32 v[108:109], s[64:65], v106, s3, v[44:45]
	v_lshlrev_b64 v[102:103], 9, v[148:149]
	v_mov_b32_e32 v153, v43
	v_mad_i32_i24 v109, v107, s3, v109
	v_lshl_add_u64 v[102:103], s[6:7], 0, v[102:103]
	v_lshl_add_u64 v[104:105], v[104:105], 0, v[152:153]
	v_lshl_add_u64 v[106:107], v[108:109], 0, s[62:63]
	v_lshl_add_u64 v[106:107], v[106:107], 0, v[152:153]
	global_load_dwordx4 v[118:121], v[104:105], off offset:512
	global_load_dwordx4 v[154:157], v[106:107], off offset:512
	v_lshl_add_u64 v[102:103], v[102:103], 0, s[62:63]
	v_lshlrev_b32_e32 v142, 1, v114
	v_lshl_add_u64 v[114:115], v[102:103], 0, v[142:143]
	global_load_dwordx4 v[106:109], v[114:115], off
	global_load_dwordx4 v[102:105], v[114:115], off offset:64
	s_waitcnt vmcnt(0)
	s_branch .Lp_382
.Lp_382:
	v_mov_b32_e32 v47, 0
	v_mov_b32_e32 v51, v0
	s_and_b32 s18, s14, 3
	s_ashr_i32 s16, s14, 7
	s_lshl_b32 s14, s14, 5
	v_ashrrev_i32_e32 v2, 2, v51
	s_ashr_i32 s17, s16, 31
	s_and_b32 s14, s14, 0xf80
	v_bfi_b32 v2, -16, v2, v51
	s_lshl_b32 s19, s18, 15
	s_add_u32 s20, s10, s19
	v_ashrrev_i32_e32 v3, 31, v2
	v_lshrrev_b32_e32 v6, 1, v51
	s_addc_u32 s21, s11, 0
	v_lshlrev_b64 v[4:5], 8, v[2:3]
	v_and_b32_e32 v62, 24, v6
	v_lshl_add_u64 v[4:5], s[20:21], 0, v[4:5]
	v_lshlrev_b32_e32 v42, 1, v62
	s_lshl_b64 s[16:17], s[16:17], 12
	v_lshl_add_u64 v[4:5], v[4:5], 0, v[42:43]
	s_or_b32 s16, s16, s14
	s_lshl_b32 s14, s18, 7
	v_add_u32_e32 v4, s14, v2
	v_ashrrev_i32_e32 v5, 31, v4
	v_lshl_add_u64 v[4:5], v[4:5], 2, s[12:13]
	v_and_b32_e32 v50, 16, v51
	v_lshrrev_b32_e32 v4, 2, v51
	v_ashrrev_i32_e32 v58, 3, v51
	v_and_or_b32 v14, v4, 8, v50
	v_lshlrev_b32_e32 v4, 4, v51
	v_ashrrev_i32_e32 v59, 31, v58
	v_and_b32_e32 v52, 0x70, v4
	v_lshl_add_u64 v[4:5], s[16:17], 0, v[58:59]
	v_mad_u64_u32 v[6:7], s[20:21], v4, s3, v[44:45]
	v_mad_i32_i24 v7, v5, s3, v7
	v_lshl_add_u64 v[4:5], v[6:7], 0, s[14:15]
	v_add_u32_e32 v6, 0x200, v51
	v_ashrrev_i32_e32 v60, 3, v6
	v_ashrrev_i32_e32 v61, 31, v60
	v_lshl_add_u64 v[6:7], s[16:17], 0, v[60:61]
	v_lshl_add_u64 v[48:49], s[16:17], 0, v[2:3]
	v_mad_u64_u32 v[8:9], s[16:17], v6, s3, v[44:45]
	v_lshlrev_b64 v[2:3], 9, v[48:49]
	v_mov_b32_e32 v53, v43
	v_mad_i32_i24 v9, v7, s3, v9
	v_lshl_add_u64 v[2:3], s[6:7], 0, v[2:3]
	v_lshl_add_u64 v[4:5], v[4:5], 0, v[52:53]
	v_lshl_add_u64 v[6:7], v[8:9], 0, s[14:15]
	v_lshl_add_u64 v[6:7], v[6:7], 0, v[52:53]
	v_lshl_add_u64 v[2:3], v[2:3], 0, s[14:15]
	v_lshlrev_b32_e32 v42, 1, v14
	v_lshl_add_u64 v[14:15], v[2:3], 0, v[42:43]
	s_waitcnt vmcnt(2)
	v_mov_b32_e32 v38, v138
	v_mov_b32_e32 v39, v139
	v_mov_b32_e32 v40, v140
	v_mov_b32_e32 v41, v141
	v_mov_b32_e32 v34, v134
	v_mov_b32_e32 v35, v135
	v_mov_b32_e32 v36, v136
	v_mov_b32_e32 v37, v137
	v_mov_b32_e32 v22, v122
	v_mov_b32_e32 v23, v123
	v_mov_b32_e32 v24, v124
	v_mov_b32_e32 v25, v125
	v_mov_b32_e32 v10, v110
	v_mov_b32_e32 v11, v111
	v_mov_b32_e32 v12, v112
	v_mov_b32_e32 v13, v113
	v_mov_b32_e32 v46, v146
	v_mov_b32_e32 v18, v118
	v_mov_b32_e32 v19, v119
	v_mov_b32_e32 v20, v120
	v_mov_b32_e32 v21, v121
	v_mov_b32_e32 v54, v154
	v_mov_b32_e32 v55, v155
	v_mov_b32_e32 v56, v156
	v_mov_b32_e32 v57, v157
	v_mov_b32_e32 v6, v106
	v_mov_b32_e32 v7, v107
	v_mov_b32_e32 v8, v108
	v_mov_b32_e32 v9, v109
	v_mov_b32_e32 v2, v102
	v_mov_b32_e32 v3, v103
	v_mov_b32_e32 v4, v104
	v_mov_b32_e32 v5, v105
	s_and_saveexec_b64 s[60:61], s[44:45]
	s_cbranch_execz .Lg_noatom_p
	v_mov_b32_e32 v67, 1
	global_atomic_add v67, v43, v67, s[8:9] sc0
.Lg_noatom_p:
	s_or_b64 exec, exec, s[60:61]
	v_bfe_u32 v59, v51, 2, 2
	v_ashrrev_i32_e32 v53, 7, v51
	v_add_u32_e32 v52, 16, v52
	v_mov_b32_e32 v26, v43
	v_mov_b32_e32 v27, v43
	v_mov_b32_e32 v28, v43
	v_mov_b32_e32 v29, v43
	v_lshlrev_b32_e32 v51, 2, v51
	v_or_b32_e32 v62, v62, v59
	v_mad_u64_u32 v[58:59], s[16:17], v58, s22, v[52:53]
	v_mov_b64_e32 v[32:33], v[28:29]
	v_mov_b64_e32 v[14:15], v[26:27]
	v_and_b32_e32 v51, 12, v51
	v_mad_u64_u32 v[60:61], s[16:17], v60, s22, v[52:53]
	v_mov_b64_e32 v[30:31], v[26:27]
	v_mov_b64_e32 v[16:17], v[28:29]
	v_cmp_lt_i32_e32 vcc, -1, v53
	v_lshlrev_b32_e32 v51, 1, v51
	v_mul_u32_u24_e32 v52, 0x90, v62
	ds_write_b128 v58, v[18:21]
	ds_write_b128 v60, v[54:57]
	v_mov_b64_e32 v[18:19], v[26:27]
	v_mov_b64_e32 v[20:21], v[28:29]
	s_waitcnt lgkmcnt(0)
	s_and_saveexec_b64 s[60:61], s[44:45]
	s_cbranch_execz .Lp_pub
	s_waitcnt vmcnt(0)
	ds_write_b32 v43, v67 offset:8
.Lp_pub:
	s_mov_b64 exec, s[60:61]
	s_waitcnt lgkmcnt(0)
	s_barrier
	ds_read_b32 v66, v43 offset:8
	s_waitcnt lgkmcnt(0)
	v_readfirstlane_b32 s70, v66
	s_cmpk_lt_i32 s70, 0x200
	s_cbranch_scc0 .Lp_nopf
	s_mov_b32 s62, s70
	s_mov_b32 s63, 0
	v_mov_b32_e32 v143, 0
	v_mov_b32_e32 v147, 0
	v_mov_b32_e32 v151, v0
	s_and_b32 s66, s62, 3
	s_ashr_i32 s64, s62, 7
	s_lshl_b32 s62, s62, 5
	v_ashrrev_i32_e32 v102, 2, v151
	s_ashr_i32 s65, s64, 31
	s_and_b32 s62, s62, 0xf80
	v_bfi_b32 v102, -16, v102, v151
	s_lshl_b32 s67, s66, 15
	s_add_u32 s68, s10, s67
	v_ashrrev_i32_e32 v103, 31, v102
	v_lshrrev_b32_e32 v106, 1, v151
	s_addc_u32 s69, s11, 0
	v_lshlrev_b64 v[104:105], 8, v[102:103]
	v_and_b32_e32 v162, 24, v106
	v_lshl_add_u64 v[104:105], s[68:69], 0, v[104:105]
	v_lshlrev_b32_e32 v142, 1, v162
	s_lshl_b64 s[64:65], s[64:65], 12
	v_lshl_add_u64 v[104:105], v[104:105], 0, v[142:143]
	s_or_b32 s64, s64, s62
	s_lshl_b32 s62, s66, 7
	global_load_dwordx4 v[138:141], v[104:105], off
	global_load_dwordx4 v[134:137], v[104:105], off offset:64
	global_load_dwordx4 v[122:125], v[104:105], off offset:128
	global_load_dwordx4 v[110:113], v[104:105], off offset:192
	v_add_u32_e32 v104, s62, v102
	v_ashrrev_i32_e32 v105, 31, v104
	v_lshl_add_u64 v[104:105], v[104:105], 2, s[12:13]
	global_load_dword v146, v[104:105], off
	v_and_b32_e32 v150, 16, v151
	v_lshrrev_b32_e32 v104, 2, v151
	v_ashrrev_i32_e32 v158, 3, v151
	v_and_or_b32 v114, v104, 8, v150
	v_lshlrev_b32_e32 v104, 4, v151
	v_ashrrev_i32_e32 v159, 31, v158
	v_and_b32_e32 v152, 0x70, v104
	v_lshl_add_u64 v[104:105], s[64:65], 0, v[158:159]
	v_mad_u64_u32 v[106:107], s[68:69], v104, s3, v[44:45]
	v_mad_i32_i24 v107, v105, s3, v107
	v_lshl_add_u64 v[104:105], v[106:107], 0, s[62:63]
	v_add_u32_e32 v106, 0x200, v151
	v_ashrrev_i32_e32 v160, 3, v106
	v_ashrrev_i32_e32 v161, 31, v160
	v_lshl_add_u64 v[106:107], s[64:65], 0, v[160:161]
	v_lshl_add_u64 v[148:149], s[64:65], 0, v[102:103]
	v_mad_u64_u32 v[108:109], s[64:65], v106, s3, v[44:45]
	v_lshlrev_b64 v[102:103], 9, v[148:149]
	v_mov_b32_e32 v153, v43
	v_mad_i32_i24 v109, v107, s3, v109
	v_lshl_add_u64 v[102:103], s[6:7], 0, v[102:103]
	v_lshl_add_u64 v[104:105], v[104:105], 0, v[152:153]
	v_lshl_add_u64 v[106:107], v[108:109], 0, s[62:63]
	v_lshl_add_u64 v[106:107], v[106:107], 0, v[152:153]
	global_load_dwordx4 v[118:121], v[104:105], off offset:512
	global_load_dwordx4 v[154:157], v[106:107], off offset:512
	v_lshl_add_u64 v[102:103], v[102:103], 0, s[62:63]
	v_lshlrev_b32_e32 v142, 1, v114
	v_lshl_add_u64 v[114:115], v[102:103], 0, v[142:143]
	global_load_dwordx4 v[106:109], v[114:115], off
	global_load_dwordx4 v[102:105], v[114:115], off offset:64
.Lp_nopf:
	s_and_saveexec_b64 s[16:17], vcc
	s_cbranch_execz .LBB0_390_p
	v_add3_u32 v26, 16, v52, v51
	ds_read_b64_tr_b16 v[14:15], v26
	ds_read_b64_tr_b16 v[16:17], v26 offset:576
	ds_read_b64_tr_b16 v[20:21], v26 offset:608
	ds_read_b64_tr_b16 v[18:19], v26 offset:32
	ds_read_b64_tr_b16 v[54:55], v26 offset:64
	ds_read_b64_tr_b16 v[58:59], v26 offset:96
	ds_read_b64_tr_b16 v[56:57], v26 offset:640
	ds_read_b64_tr_b16 v[60:61], v26 offset:672
	s_waitcnt lgkmcnt(6)
	v_mfma_f32_16x16x32_bf16 v[26:29], v[14:17], v[38:41], 0
	s_waitcnt lgkmcnt(4)
	v_mfma_f32_16x16x32_bf16 v[30:33], v[18:21], v[38:41], 0
	s_waitcnt lgkmcnt(1)
	v_mfma_f32_16x16x32_bf16 v[14:17], v[54:57], v[38:41], 0
	s_waitcnt lgkmcnt(0)
	v_mfma_f32_16x16x32_bf16 v[18:21], v[58:61], v[38:41], 0
	s_or_b64 exec, exec, s[16:17]
	v_cmp_lt_i32_e32 vcc, 0, v53
	s_and_saveexec_b64 s[16:17], vcc
	s_cbranch_execnz .LBB0_391_p

.LBB0_394_p:
	s_or_b64 exec, exec, s[16:17]
	v_and_b32_e32 v13, 64, v1
	v_xor_b32_e32 v12, 16, v1
	v_add_u32_e32 v13, 64, v13
	v_cmp_lt_i32_e32 vcc, v12, v13
	s_lshl_b32 s14, s18, 6
	v_lshlrev_b64 v[10:11], 11, v[48:49]
	v_cndmask_b32_e32 v12, v1, v12, vcc
	v_cmp_eq_u32_e32 vcc, 0, v50
	v_lshlrev_b32_e32 v34, 2, v12
	v_lshl_add_u64 v[10:11], s[4:5], 0, v[10:11]
	v_cndmask_b32_e32 v22, v27, v31, vcc
	v_cndmask_b32_e32 v23, v26, v30, vcc
	v_cndmask_b32_e32 v12, v29, v33, vcc
	v_cndmask_b32_e32 v13, v28, v32, vcc
	ds_bpermute_b32 v36, v34, v22
	ds_bpermute_b32 v37, v34, v23
	ds_bpermute_b32 v24, v34, v12
	ds_bpermute_b32 v35, v34, v13
	s_lshl_b32 s14, s14, 1
	s_waitcnt lgkmcnt(3)
	v_cndmask_b32_e32 v23, v36, v27, vcc
	s_waitcnt lgkmcnt(2)
	v_cndmask_b32_e32 v22, v37, v26, vcc
	s_waitcnt lgkmcnt(1)
	v_cndmask_b32_e32 v13, v24, v29, vcc
	s_waitcnt lgkmcnt(0)
	v_cndmask_b32_e32 v12, v35, v28, vcc
	v_lshlrev_b32_e32 v28, 16, v6
	v_and_b32_e32 v29, 0xffff0000, v6
	v_pk_add_f32 v[22:23], v[46:47], v[22:23] op_sel_hi:[0,1]
	v_pk_mul_f32 v[22:23], v[22:23], v[28:29]
	v_pk_add_f32 v[12:13], v[46:47], v[12:13] op_sel_hi:[0,1]
	v_cvt_pk_bf16_f32 v6, v22, v23
	v_lshlrev_b32_e32 v22, 16, v7
	v_and_b32_e32 v23, 0xffff0000, v7
	v_cndmask_b32_e32 v27, v31, v36, vcc
	v_cndmask_b32_e32 v26, v30, v37, vcc
	v_pk_mul_f32 v[12:13], v[12:13], v[22:23]
	v_pk_add_f32 v[22:23], v[46:47], v[26:27] op_sel_hi:[0,1]
	v_cvt_pk_bf16_f32 v7, v12, v13
	v_lshlrev_b32_e32 v12, 16, v8
	v_and_b32_e32 v13, 0xffff0000, v8
	v_cndmask_b32_e32 v25, v33, v24, vcc
	v_cndmask_b32_e32 v24, v32, v35, vcc
	v_pk_mul_f32 v[12:13], v[22:23], v[12:13]
	v_pk_add_f32 v[22:23], v[46:47], v[24:25] op_sel_hi:[0,1]
	v_cvt_pk_bf16_f32 v8, v12, v13
	v_lshlrev_b32_e32 v12, 16, v9
	v_and_b32_e32 v13, 0xffff0000, v9
	v_pk_mul_f32 v[12:13], v[22:23], v[12:13]
	v_cndmask_b32_e32 v22, v15, v19, vcc
	v_cndmask_b32_e32 v23, v14, v18, vcc
	v_cvt_pk_bf16_f32 v9, v12, v13
	v_cndmask_b32_e32 v12, v17, v21, vcc
	v_cndmask_b32_e32 v13, v16, v20, vcc
	ds_bpermute_b32 v22, v34, v22
	ds_bpermute_b32 v23, v34, v23
	ds_bpermute_b32 v12, v34, v12
	ds_bpermute_b32 v24, v34, v13
	v_lshl_add_u64 v[10:11], v[10:11], 0, s[14:15]
	v_lshl_add_u64 v[10:11], v[10:11], 0, v[42:43]
	global_store_dwordx4 v[10:11], v[6:9], off
	s_waitcnt lgkmcnt(1)
	v_cndmask_b32_e32 v13, v21, v12, vcc
	v_cndmask_b32_e32 v9, v22, v15, vcc
	v_cndmask_b32_e32 v8, v23, v14, vcc
	v_cndmask_b32_e32 v7, v12, v17, vcc
	s_waitcnt lgkmcnt(0)
	v_cndmask_b32_e32 v6, v24, v16, vcc
	v_lshlrev_b32_e32 v16, 16, v2
	v_and_b32_e32 v17, 0xffff0000, v2
	v_pk_add_f32 v[8:9], v[46:47], v[8:9] op_sel_hi:[0,1]
	v_pk_mul_f32 v[8:9], v[8:9], v[16:17]
	v_pk_add_f32 v[6:7], v[46:47], v[6:7] op_sel_hi:[0,1]
	v_cvt_pk_bf16_f32 v2, v8, v9
	v_lshlrev_b32_e32 v8, 16, v3
	v_and_b32_e32 v9, 0xffff0000, v3
	v_cndmask_b32_e32 v15, v19, v22, vcc
	v_cndmask_b32_e32 v14, v18, v23, vcc
	v_pk_mul_f32 v[6:7], v[6:7], v[8:9]
	v_pk_add_f32 v[8:9], v[46:47], v[14:15] op_sel_hi:[0,1]
	v_cvt_pk_bf16_f32 v3, v6, v7
	v_lshlrev_b32_e32 v6, 16, v4
	v_and_b32_e32 v7, 0xffff0000, v4
	v_cndmask_b32_e32 v12, v20, v24, vcc
	v_pk_mul_f32 v[6:7], v[8:9], v[6:7]
	v_pk_add_f32 v[8:9], v[46:47], v[12:13] op_sel_hi:[0,1]
	v_cvt_pk_bf16_f32 v4, v6, v7
	v_lshlrev_b32_e32 v6, 16, v5
	v_and_b32_e32 v7, 0xffff0000, v5
	v_pk_mul_f32 v[6:7], v[8:9], v[6:7]
	s_nop 0
	v_cvt_pk_bf16_f32 v5, v6, v7
	global_store_dwordx4 v[10:11], v[2:5], off offset:64
	s_barrier
	s_mov_b32 s14, s70
	s_cmpk_lt_i32 s14, 0x200
	s_cbranch_scc1 .Lp_382
	s_branch .LBB0_396
